# sparse phase job queue also split into 8 per-XCD sub-queues with stealing
# speedup vs baseline: 1.0029x; 1.0018x over previous
; DI void phase_sparse(const Params& p, int layer, int phase, unsigned char* smem) {
;   u32* ctr = p.ctr + phase;
;   for (;;) {
;     ...
;   switch (s) {
;     case 0: phase_g1(p, layer, smem); break;
;     case 1: phase_attn(p, layer, ph + 16 * rep, smem); break;
;     case 2: phase_sparse(p, layer, ph + 16 * rep, smem); break;
.LBB0_301:
	s_and_b64 vcc, exec, s[2:3]
	s_cbranch_vccz .LBB0_952
	v_readlane_b32 s2, v252, 29
	s_cmp_gt_i32 s2, 0
	s_mov_b64 s[2:3], -1
	s_cbranch_scc0 .LBB0_950
	v_readlane_b32 s2, v252, 29
	s_cmp_gt_i32 s2, 1
	s_mov_b64 s[2:3], -1
	s_cbranch_scc0 .LBB0_355
	v_readlane_b32 s2, v252, 26
	v_readlane_b32 s3, v252, 27
	s_mov_b32 s4, s2
	s_ashr_i32 s5, s2, 31
	v_writelane_b32 v252, s2, 26
	s_nop 1
	v_writelane_b32 v252, s3, 27
	s_and_b32 s4, s4, 8
	s_add_i32 s4, s4, 32
	s_getreg_b32 s2, hwreg(HW_REG_XCC_ID, 0, 4)
	s_and_b32 s2, s2, 7
	s_mov_b32 s3, 0
	s_nop 0
	v_writelane_b32 v252, s2, 62
	v_writelane_b32 v252, s3, 61
	s_lshl_b64 s[2:3], s[4:5], 2
	s_load_dwordx2 s[4:5], s[0:1], 0x178
	s_waitcnt lgkmcnt(0)
	s_add_u32 s2, s4, s2
	s_addc_u32 s3, s5, s3
	v_writelane_b32 v252, s2, 32
	s_nop 1
	v_writelane_b32 v252, s3, 33
	s_branch .LBB0_308

; DI int next_job(u32* ctr, unsigned char* smem) {
;   int* sj = (int*)(smem + SJOB_OFF);
;   __syncthreads();
;   if (threadIdx.x == 0) *sj = (int)atomicAdd(ctr, 1u);
.LBB0_308:
	s_mov_b64 s[2:3], exec
	v_readlane_b32 s4, v253, 1
	v_readlane_b32 s5, v253, 2
	s_and_b64 s[4:5], s[2:3], s[4:5]
	s_mov_b64 exec, s[4:5]
	s_cbranch_execz .Lsx_pre
	v_readlane_b32 s6, v252, 62
	v_readlane_b32 s7, v252, 61
	v_readlane_b32 s4, v252, 32
	v_readlane_b32 s5, v252, 33
	s_nop 0
	s_cmp_lt_u32 s7, 8
	s_cbranch_scc0 .Lsx_pre
	s_lshl_b32 vcc_hi, s6, 2
	s_nop 0
	s_add_u32 s4, s4, vcc_hi
	s_addc_u32 s5, s5, 0
	v_mov_b32_e32 v2, 1
	s_nop 1
	global_atomic_add v2, v1, v2, s[4:5] sc0

; DI int next_job(u32* ctr, unsigned char* smem) {
;   int* sj = (int*)(smem + SJOB_OFF);
;   __syncthreads();
;   if (threadIdx.x == 0) *sj = (int)atomicAdd(ctr, 1u);
;   __syncthreads();
;   return *sj;
; }
; DI void phase_sparse(const Params& p, int layer, int phase, unsigned char* smem) {
;     ...
;     const int jp = next_job(ctr, smem);
;     if (jp >= 528) break;
;     int half = threadIdx.x >> 8; asm volatile("" : "+v"(half));
;     unsigned char* sm = smem + half * HALF_BYTES;
;     const int job = 2 * jp + half;
;     const int qb = 32 - job / 32, r = job & 31;
.Lsx_loop:
	s_cmp_lt_u32 s7, 8
	s_cbranch_scc0 .Lsx_done
	v_readlane_b32 s4, v252, 32
	v_readlane_b32 s5, v252, 33
	s_lshl_b32 vcc_hi, s6, 2
	s_nop 0
	s_add_u32 s4, s4, vcc_hi
	s_addc_u32 s5, s5, 0
	v_mov_b32_e32 v2, 1
	s_nop 1
	global_atomic_add v2, v1, v2, s[4:5] sc0
.Lsx_wait:
	s_waitcnt vmcnt(0)
	v_readfirstlane_b32 vcc_lo, v2
	s_nop 0
	s_cmpk_lt_u32 vcc_lo, 0x42
	s_cbranch_scc1 .Lsx_got
	s_add_i32 s6, s6, 1
	s_and_b32 s6, s6, 7
	s_add_i32 s7, s7, 1
	s_branch .Lsx_loop
.Lsx_got:
	s_lshr_b32 vcc_hi, vcc_lo, 1
	s_lshl_b32 vcc_hi, vcc_hi, 4
	s_and_b32 vcc_lo, vcc_lo, 1
	s_lshl_b32 vcc_lo, vcc_lo, 3
	s_add_i32 vcc_lo, vcc_lo, vcc_hi
	s_add_i32 vcc_lo, vcc_lo, s6
	s_branch .Lsx_wr
.Lsx_done:
	s_movk_i32 vcc_lo, 0x210
.Lsx_wr:
	v_writelane_b32 v252, s6, 62
	v_writelane_b32 v252, s7, 61
	v_mov_b32_e32 v0, vcc_lo
	ds_write_b32 v200, v0
